# GQKV small_gemm_tile: 24+8 fragment loads issued up front with counted waits instead of load-by-load vmcnt(0)
# speedup vs baseline: 1.0045x; 1.0025x over previous
; #define MFMA16(a, b, c) __builtin_amdgcn_mfma_f32_16x16x32_bf16((a), (b), (c), 0, 0, 0)
; #define MFMA16(a, b, c) __builtin_amdgcn_mfma_f32_16x16x32_bf16((a), (b), (c), 0, 0, 0)
; template <int MODE>
; __device__ __forceinline__ void small_gemm_tile(const Ctx& c, const bf16_t* A, const bf16_t* Bt, int K, int tm, int tn, bf16_t* O, int ldo, const float* bias, float* pss) {
;     ...
;     const bf16_t* ap = A + (size_t)(64 * tm + c16) * K + w * kw + 8 * q;
;     const bf16_t* bp = Bt + (size_t)(64 * tn + c16) * K + w * kw + 8 * q;
; #pragma unroll 4
;     for (int ks = 0; ks < nks; ++ks) {
;         bf16x8 af[4], bfr[4];
; #pragma unroll
;         for (int mt = 0; mt < 4; ++mt) af[mt] = *(const bf16x8*)(ap + (size_t)mt * 16 * K + ks * 32);
; #pragma unroll
;         for (int nt = 0; nt < 4; ++nt) bfr[nt] = *(const bf16x8*)(bp + (size_t)nt * 16 * K + ks * 32);
; #pragma unroll
;         for (int mt = 0; mt < 4; ++mt)
; #pragma unroll
;             for (int nt = 0; nt < 4; ++nt) acc[mt][nt] = MFMA16(af[mt], bfr[nt], acc[mt][nt]);
;     }
.LBB0_74:
	s_mul_hi_i32 s2, s10, 0x2aaaaaab
	s_lshr_b32 s3, s2, 31
	s_ashr_i32 s2, s2, 2
	s_add_i32 s2, s2, s3
	s_lshl_b32 s7, s2, 6
	s_mulk_i32 s2, 0xfa00
	s_add_i32 s6, s2, s9
	v_add_u32_e32 v8, s6, v19
	v_ashrrev_i32_e32 v9, 31, v8
	v_or_b32_e32 v4, s7, v19
	v_lshlrev_b64 v[8:9], 11, v[8:9]
	v_ashrrev_i32_e32 v5, 31, v4
	v_lshl_add_u64 v[32:33], v[16:17], 0, v[8:9]
	v_lshlrev_b64 v[4:5], 11, v[4:5]
	s_mov_b64 s[2:3], 0x8000
	v_lshl_add_u64 v[30:31], v[0:1], 0, v[4:5]
	s_mov_b32 s11, 0x18000
	v_lshl_add_u64 v[36:37], v[32:33], 0, s[2:3]
	v_lshl_add_u64 v[34:35], v[30:31], 0, s[2:3]
	v_lshl_add_u64 v[24:25], v[36:37], 0, s[2:3]
	v_lshl_add_u64 v[22:23], v[34:35], 0, s[2:3]
	v_lshl_add_u64 v[28:29], v[24:25], 0, s[2:3]
	v_lshl_add_u64 v[26:27], v[22:23], 0, s[2:3]
	global_load_dwordx4 v[4:7], v[30:31], off
	global_load_dwordx4 v[8:11], v[34:35], off
	global_load_dwordx4 v[12:15], v[22:23], off
	global_load_dwordx4 v[120:123], v[26:27], off
	global_load_dwordx4 v[124:127], v[32:33], off
	global_load_dwordx4 v[128:131], v[36:37], off
	global_load_dwordx4 v[132:135], v[24:25], off
	global_load_dwordx4 v[136:139], v[28:29], off
	global_load_dwordx4 v[140:143], v[30:31], off offset:64
	global_load_dwordx4 v[144:147], v[34:35], off offset:64
	global_load_dwordx4 v[148:151], v[22:23], off offset:64
	global_load_dwordx4 v[166:169], v[26:27], off offset:64
	global_load_dwordx4 v[170:173], v[32:33], off offset:64
	global_load_dwordx4 v[174:177], v[36:37], off offset:64
	global_load_dwordx4 v[178:181], v[24:25], off offset:64
	global_load_dwordx4 v[182:185], v[28:29], off offset:64
	global_load_dwordx4 v[186:189], v[30:31], off offset:128
	global_load_dwordx4 v[190:193], v[34:35], off offset:128
	global_load_dwordx4 v[194:197], v[22:23], off offset:128
	global_load_dwordx4 v[198:201], v[26:27], off offset:128
	global_load_dwordx4 v[202:205], v[32:33], off offset:128
	global_load_dwordx4 v[206:209], v[36:37], off offset:128
	global_load_dwordx4 v[210:213], v[24:25], off offset:128
	global_load_dwordx4 v[214:217], v[28:29], off offset:128
	v_add_u32_e32 v218, 0x1040, v3
	v_add_u32_e32 v219, 0x2080, v3
	v_add_u32_e32 v220, 0x30c0, v3
	s_waitcnt vmcnt(16)
	v_mfma_f32_16x16x32_bf16 v[56:59], v[4:7], v[124:127], 0
	v_mfma_f32_16x16x32_bf16 v[60:63], v[4:7], v[128:131], 0
	v_mfma_f32_16x16x32_bf16 v[64:67], v[4:7], v[132:135], 0
	v_mfma_f32_16x16x32_bf16 v[68:71], v[4:7], v[136:139], 0
	v_mfma_f32_16x16x32_bf16 v[72:75], v[8:11], v[124:127], 0
	v_mfma_f32_16x16x32_bf16 v[76:79], v[8:11], v[128:131], 0
	v_mfma_f32_16x16x32_bf16 v[80:83], v[8:11], v[132:135], 0
	v_mfma_f32_16x16x32_bf16 v[84:87], v[8:11], v[136:139], 0
	v_mfma_f32_16x16x32_bf16 v[88:91], v[12:15], v[124:127], 0
	v_mfma_f32_16x16x32_bf16 v[92:95], v[12:15], v[128:131], 0
	v_mfma_f32_16x16x32_bf16 v[96:99], v[12:15], v[132:135], 0
	v_mfma_f32_16x16x32_bf16 v[100:103], v[12:15], v[136:139], 0
	v_mfma_f32_16x16x32_bf16 v[104:107], v[120:123], v[124:127], 0
	v_mfma_f32_16x16x32_bf16 v[108:111], v[120:123], v[128:131], 0
	v_mfma_f32_16x16x32_bf16 v[112:115], v[120:123], v[132:135], 0
	v_mfma_f32_16x16x32_bf16 v[116:119], v[120:123], v[136:139], 0
	global_load_dwordx4 v[4:7], v[30:31], off offset:192
	global_load_dwordx4 v[8:11], v[34:35], off offset:192
	global_load_dwordx4 v[12:15], v[22:23], off offset:192
	global_load_dwordx4 v[120:123], v[26:27], off offset:192
	global_load_dwordx4 v[124:127], v[32:33], off offset:192
	global_load_dwordx4 v[128:131], v[36:37], off offset:192
	global_load_dwordx4 v[132:135], v[24:25], off offset:192
	global_load_dwordx4 v[136:139], v[28:29], off offset:192
	s_waitcnt vmcnt(16)
	v_mfma_f32_16x16x32_bf16 v[56:59], v[140:143], v[170:173], v[56:59]
	v_mfma_f32_16x16x32_bf16 v[60:63], v[140:143], v[174:177], v[60:63]
	v_mfma_f32_16x16x32_bf16 v[64:67], v[140:143], v[178:181], v[64:67]
	v_mfma_f32_16x16x32_bf16 v[68:71], v[140:143], v[182:185], v[68:71]
	v_mfma_f32_16x16x32_bf16 v[72:75], v[144:147], v[170:173], v[72:75]
	v_mfma_f32_16x16x32_bf16 v[76:79], v[144:147], v[174:177], v[76:79]
	v_mfma_f32_16x16x32_bf16 v[80:83], v[144:147], v[178:181], v[80:83]
	v_mfma_f32_16x16x32_bf16 v[84:87], v[144:147], v[182:185], v[84:87]
	v_mfma_f32_16x16x32_bf16 v[88:91], v[148:151], v[170:173], v[88:91]
	v_mfma_f32_16x16x32_bf16 v[92:95], v[148:151], v[174:177], v[92:95]
	v_mfma_f32_16x16x32_bf16 v[96:99], v[148:151], v[178:181], v[96:99]
	v_mfma_f32_16x16x32_bf16 v[100:103], v[148:151], v[182:185], v[100:103]
	v_mfma_f32_16x16x32_bf16 v[104:107], v[166:169], v[170:173], v[104:107]
	v_mfma_f32_16x16x32_bf16 v[108:111], v[166:169], v[174:177], v[108:111]
	v_mfma_f32_16x16x32_bf16 v[112:115], v[166:169], v[178:181], v[112:115]
	v_mfma_f32_16x16x32_bf16 v[116:119], v[166:169], v[182:185], v[116:119]
	s_waitcnt vmcnt(8)
; #define MFMA16(a, b, c) __builtin_amdgcn_mfma_f32_16x16x32_bf16((a), (b), (c), 0, 0, 0)
; #define MFMA16(a, b, c) __builtin_amdgcn_mfma_f32_16x16x32_bf16((a), (b), (c), 0, 0, 0)
; template <int MODE>
; __device__ __forceinline__ void small_gemm_tile(const Ctx& c, const bf16_t* A, const bf16_t* Bt, int K, int tm, int tn, bf16_t* O, int ldo, const float* bias, float* pss) {
;     ...
;     for (int ks = 0; ks < nks; ++ks) {
;         bf16x8 af[4], bfr[4];
; #pragma unroll
;         for (int mt = 0; mt < 4; ++mt) af[mt] = *(const bf16x8*)(ap + (size_t)mt * 16 * K + ks * 32);
; #pragma unroll
;         for (int nt = 0; nt < 4; ++nt) bfr[nt] = *(const bf16x8*)(bp + (size_t)nt * 16 * K + ks * 32);
; #pragma unroll
;         for (int mt = 0; mt < 4; ++mt)
; #pragma unroll
;             for (int nt = 0; nt < 4; ++nt) acc[mt][nt] = MFMA16(af[mt], bfr[nt], acc[mt][nt]);
;     }
; #pragma unroll
;     for (int mt = 0; mt < 4; ++mt)
; #pragma unroll
;         for (int nt = 0; nt < 4; ++nt)
; #pragma unroll
;             for (int r = 0; r < 4; ++r) P[(w * 64 + mt * 16 + 4 * q + r) * 65 + nt * 16 + c16] = acc[mt][nt][r];
;     __syncthreads();
	v_mfma_f32_16x16x32_bf16 v[56:59], v[186:189], v[202:205], v[56:59]
	v_mfma_f32_16x16x32_bf16 v[60:63], v[186:189], v[206:209], v[60:63]
	v_mfma_f32_16x16x32_bf16 v[64:67], v[186:189], v[210:213], v[64:67]
	v_mfma_f32_16x16x32_bf16 v[68:71], v[186:189], v[214:217], v[68:71]
	v_mfma_f32_16x16x32_bf16 v[72:75], v[190:193], v[202:205], v[72:75]
	v_mfma_f32_16x16x32_bf16 v[76:79], v[190:193], v[206:209], v[76:79]
	v_mfma_f32_16x16x32_bf16 v[80:83], v[190:193], v[210:213], v[80:83]
	v_mfma_f32_16x16x32_bf16 v[84:87], v[190:193], v[214:217], v[84:87]
	v_mfma_f32_16x16x32_bf16 v[88:91], v[194:197], v[202:205], v[88:91]
	v_mfma_f32_16x16x32_bf16 v[92:95], v[194:197], v[206:209], v[92:95]
	v_mfma_f32_16x16x32_bf16 v[96:99], v[194:197], v[210:213], v[96:99]
	v_mfma_f32_16x16x32_bf16 v[100:103], v[194:197], v[214:217], v[100:103]
	v_mfma_f32_16x16x32_bf16 v[104:107], v[198:201], v[202:205], v[104:107]
	v_mfma_f32_16x16x32_bf16 v[108:111], v[198:201], v[206:209], v[108:111]
	v_mfma_f32_16x16x32_bf16 v[112:115], v[198:201], v[210:213], v[112:115]
	v_mfma_f32_16x16x32_bf16 v[116:119], v[198:201], v[214:217], v[116:119]
	s_waitcnt vmcnt(0)
	v_mfma_f32_16x16x32_bf16 v[56:59], v[4:7], v[124:127], v[56:59]
	v_mfma_f32_16x16x32_bf16 v[60:63], v[4:7], v[128:131], v[60:63]
	v_mfma_f32_16x16x32_bf16 v[64:67], v[4:7], v[132:135], v[64:67]
	v_mfma_f32_16x16x32_bf16 v[68:71], v[4:7], v[136:139], v[68:71]
	v_mfma_f32_16x16x32_bf16 v[72:75], v[8:11], v[124:127], v[72:75]
	v_mfma_f32_16x16x32_bf16 v[76:79], v[8:11], v[128:131], v[76:79]
	v_mfma_f32_16x16x32_bf16 v[80:83], v[8:11], v[132:135], v[80:83]
	v_mfma_f32_16x16x32_bf16 v[84:87], v[8:11], v[136:139], v[84:87]
	v_mfma_f32_16x16x32_bf16 v[88:91], v[12:15], v[124:127], v[88:91]
	v_mfma_f32_16x16x32_bf16 v[92:95], v[12:15], v[128:131], v[92:95]
	v_mfma_f32_16x16x32_bf16 v[96:99], v[12:15], v[132:135], v[96:99]
	v_mfma_f32_16x16x32_bf16 v[100:103], v[12:15], v[136:139], v[100:103]
	v_mfma_f32_16x16x32_bf16 v[104:107], v[120:123], v[124:127], v[104:107]
	v_mfma_f32_16x16x32_bf16 v[108:111], v[120:123], v[128:131], v[108:111]
	v_mfma_f32_16x16x32_bf16 v[112:115], v[120:123], v[132:135], v[112:115]
	v_mfma_f32_16x16x32_bf16 v[116:119], v[120:123], v[136:139], v[116:119]
	s_nop 15
	s_nop 7
	ds_write2_b32 v3, v56, v60 offset1:16
	ds_write2_b32 v3, v64, v68 offset0:32 offset1:48
	ds_write2_b32 v3, v57, v61 offset0:65 offset1:81
	ds_write2_b32 v3, v65, v69 offset0:97 offset1:113
	ds_write2_b32 v3, v58, v62 offset0:130 offset1:146
	ds_write2_b32 v3, v66, v70 offset0:162 offset1:178
	ds_write2_b32 v3, v59, v63 offset0:195 offset1:211
	ds_write2_b32 v3, v67, v71 offset0:227 offset1:243
	ds_write2_b32 v218, v72, v76 offset1:16
	ds_write2_b32 v218, v80, v84 offset0:32 offset1:48
	ds_write2_b32 v218, v73, v77 offset0:65 offset1:81
	ds_write2_b32 v218, v81, v85 offset0:97 offset1:113
	ds_write2_b32 v218, v74, v78 offset0:130 offset1:146
	ds_write2_b32 v218, v82, v86 offset0:162 offset1:178
	ds_write2_b32 v218, v75, v79 offset0:195 offset1:211
	ds_write2_b32 v218, v83, v87 offset0:227 offset1:243
	ds_write2_b32 v219, v88, v92 offset1:16
	ds_write2_b32 v219, v96, v100 offset0:32 offset1:48
	ds_write2_b32 v219, v89, v93 offset0:65 offset1:81
	ds_write2_b32 v219, v97, v101 offset0:97 offset1:113
	ds_write2_b32 v219, v90, v94 offset0:130 offset1:146
	ds_write2_b32 v219, v98, v102 offset0:162 offset1:178
	ds_write2_b32 v219, v91, v95 offset0:195 offset1:211
	ds_write2_b32 v219, v99, v103 offset0:227 offset1:243
	ds_write2_b32 v220, v104, v108 offset1:16
	ds_write2_b32 v220, v112, v116 offset0:32 offset1:48
	ds_write2_b32 v220, v105, v109 offset0:65 offset1:81
	ds_write2_b32 v220, v113, v117 offset0:97 offset1:113
	ds_write2_b32 v220, v106, v110 offset0:130 offset1:146
	ds_write2_b32 v220, v114, v118 offset0:162 offset1:178
	ds_write2_b32 v220, v107, v111 offset0:195 offset1:211
	ds_write2_b32 v220, v115, v119 offset0:227 offset1:243
	s_andn2_b64 vcc, exec, s[12:13]
	v_add_u32_e32 v4, s6, v18
	v_cndmask_b32_e64 v5, 0, 1, s[12:13]
	v_cmp_ne_u32_e64 s[2:3], 1, v5
	v_ashrrev_i32_e32 v5, 31, v4
	s_waitcnt lgkmcnt(0)
	s_barrier
	s_cbranch_vccnz .LBB0_89
	v_lshl_add_u64 v[6:7], v[4:5], 2, s[18:19]
	global_load_dword v12, v[6:7], off
	v_mov_b32_e32 v6, 0
	s_and_b64 vcc, exec, s[2:3]
	v_mov_b32_e32 v13, 0
	s_cbranch_vccnz .LBB0_77
